# group-local sync waits guarded by a run-time XCC-id check (fall back to waiting for all groups if a group is not on one XCD); full write-back everywhere
# speedup vs baseline: 1.0010x; 1.0003x over previous
.Lsyncinv_0:
	buffer_inv sc1
	s_waitcnt vmcnt(0)
	s_mov_b64 s[6:7], exec
	s_mov_b32 exec_lo, -1
	s_mov_b32 exec_hi, 0
	v_mbcnt_lo_u32_b32 v1, -1, 0
	s_and_b32 s4, s76, 7
	s_lshl_b32 s4, s4, 2
	v_lshl_add_u32 v1, v1, 5, s4
	global_load_dword v2, v1, s[2:3] offset:3072 sc1
	s_getreg_b32 s4, hwreg(HW_REG_XCC_ID, 0, 4)
	s_waitcnt vmcnt(0)
	v_cmp_ne_u32_e32 vcc, s4, v2
	s_cmp_lg_u32 vcc_lo, 0
	s_cselect_b32 s4, 1, 0
	v_writelane_b32 v254, s4, 61
	s_mov_b64 exec, s[6:7]

.LBB0_1325:
	s_or_b64 exec, exec, s[6:7]
	v_readlane_b32 s4, v254, 1
	s_add_i32 s6, s4, 4
	s_lshl_b32 s6, s6, 5
	v_readlane_b32 s4, v254, 61
	s_cmp_eq_u32 s4, 0
	s_cbranch_scc1 .Lxloc_4
	s_mov_b32 s7, 0x80000

.Lxloc_4:
	s_nop 0
	s_and_b32 s4, s76, 7
	s_lshl_b32 s4, s4, 6
	s_add_i32 s4, s4, 0x400
	s_add_u32 s2, s2, s4
	s_addc_u32 s3, s3, 0
	s_mov_b32 s7, 0x400000
	s_branch .LBB0_1327

.LBB0_1381:
	s_or_b64 exec, exec, s[6:7]
	v_readlane_b32 s4, v254, 1
	s_add_i32 s6, s4, 5
	s_lshl_b32 s6, s6, 5
	v_readlane_b32 s4, v254, 61
	s_cmp_eq_u32 s4, 0
	s_cbranch_scc1 .Lxloc_5
	s_mov_b32 s7, 0x80000

.LBB0_1453:
	s_or_b64 exec, exec, s[6:7]
	v_readlane_b32 s4, v254, 1
	s_add_i32 s6, s4, 6
	s_lshl_b32 s6, s6, 5
	v_readlane_b32 s4, v254, 61
	s_cmp_eq_u32 s4, 0
	s_cbranch_scc1 .Lxloc_6
	s_mov_b32 s7, 0x80000

.LBB0_1513:
	s_or_b64 exec, exec, s[6:7]
	v_readlane_b32 s4, v254, 1
	s_lshl_b32 s6, s4, 5
	s_mov_b32 s7, 0x80000
	s_cmp_eq_u32 s4, 28
	s_cbranch_scc1 .Ls7_glob
	v_readlane_b32 s5, v254, 61
	s_cmp_lg_u32 s5, 0
	s_cbranch_scc1 .Ls7_glob
	s_and_b32 s5, s76, 7
	s_lshl_b32 s5, s5, 6
	s_add_i32 s5, s5, 0x400
	s_add_u32 s2, s2, s5
	s_addc_u32 s3, s3, 0
